# out-proj (D1) tile k-loop ported to the LDS-DMA loop used by the in-proj tiles (accumulator pair swapped at this site); D1 sits on every chain's critical path
# speedup vs baseline: 1.0840x; 1.0060x over previous
; DI char* opq(char* q) { size_t z = 0; asm volatile("" : "+s"(z)); return q + z; }
; DI int tidx() { int t = threadIdx.x; asm volatile("" : "+v"(t)); return t; }
; #define GLOAD(dst, kt_) _Pragma("unroll") for (int i = 0; i < NCH; ++i) { dst[i] = (i < NCHW) ? ldw(i, tid >> 3, (kt_) * 64 + (tid & 7) * 8) : ldx(i - NCHW, tid >> 3, (kt_) * 64 + (tid & 7) * 8); }
; #define LSTORE(src, base) _Pragma("unroll") for (int i = 0; i < NCH; ++i) { const int c = tid + 256 * i; *(u32x4*)((base) + (c >> 3) * 144 + (c & 7) * 16) = src[i]; }
; template <int WGN, int INS, int IMS, bool DB, class LdW, class LdX>
; DI void gemm_core(f32x16 (&acc)[INS][IMS], const int KT, LdW ldw, LdX ldx, char* lds, const int tid) {
;   constexpr int WGM = 4 / WGN;
;   constexpr int WROWS = WGN * 32 * INS, XROWS = WGM * 32 * IMS, NROWS = WROWS + XROWS, NCH = NROWS / 32, NCHW = WROWS / 32, BUFB = NROWS * 144;
;   const int lane = tid & 63, wid = tid >> 6, l31 = lane & 31, hi = lane >> 5;
;   const int wn = (WGN == 2) ? (wid >> 1) : wid, wm = (WGN == 2) ? (wid & 1) : 0;
;   const int offa = (wn * 32 * INS + l31) * 144 + hi * 16;
;   const int offb = (WROWS + wm * 32 * IMS + l31) * 144 + hi * 16;
; #pragma unroll
;   for (int a = 0; a < INS; ++a)
; #pragma unroll
;     for (int b = 0; b < IMS; ++b)
; #pragma unroll
;       for (int r = 0; r < 16; ++r) acc[a][b][r] = 0.f;
;     ...
;   if (DB) {
;     u32x4 preA[NCH], preB[NCH];
;     GLOAD(preA, 0)
;     GLOAD(preB, 1)
;     __syncthreads();
;     LSTORE(preA, lds)
;     __syncthreads();
; DI void outproj_item(const Params& p, int l, int it, char* lds) {
;   char* const ws_ = opq(p.ws);
;   const int mt = (it & 7) * 16 + ((it >> 3) & 15), nt = it >> 7;
;   const u16* W = (const u16*)(ws_ + OFF_WOUT) + ((size_t)l * 1024 + nt * 256) * 1024;
;   const u16* Y = (const u16*)(ws_ + OFF_XB) + (size_t)mt * 128 * 1024;
;   f32x16 acc[4][2];
;   const int tid = tidx();
;   gemm_core<2, 4, 2, false>(acc, 16, [&](int i, int r0, int k) -> u32x4 { return *(const u32x4*)((W + i * 32768) + (unsigned)(r0 * 1024 + k)); },
;                [&](int i, int r0, int k) -> u32x4 { return *(const u32x4*)((Y + i * 32768) + (unsigned)(r0 * 1024 + k)); }, lds, tid);
.LBB0_533:
	s_mov_b64 s[0:1], 0
	s_add_u32 s28, s90, s0
	s_addc_u32 s29, s91, s1
	s_lshl_b32 s0, s27, 4
	s_and_b32 s0, s0, 0x70
	s_bfe_u32 s1, s27, 0x40003
	s_ashr_i32 s30, s27, 7
	s_or_b32 s4, s0, s1
	s_lshl_b32 s0, s30, 8
	s_ashr_i32 s1, s0, 31
	s_add_u32 s5, s28, s26
	s_addc_u32 s6, s29, 0
	s_lshl_b64 s[2:3], s[0:1], 11
	s_add_u32 s18, s5, s2
	s_addc_u32 s19, s6, s3
	s_add_u32 s2, s18, 0x1a00000
	s_addc_u32 s3, s19, 0
	s_lshl_b32 s80, s4, 7
	s_lshl_b32 s4, s4, 18
	s_add_u32 s24, s28, s4
	s_addc_u32 s25, s29, 0
	s_add_u32 s4, s24, 0x2a40000
	s_addc_u32 s5, s25, 0
	v_mov_b32_e32 v181, v176
	v_and_b32_e32 v183, 0x5f, v181
	v_lshlrev_b32_e32 v185, 4, v181
	v_and_b32_e32 v220, 63, v181
	v_lshrrev_b32_e32 v221, 6, v181
	v_lshrrev_b32_e32 v222, 3, v220
	v_readfirstlane_b32 s13, v221
	v_and_b32_e32 v223, 7, v220
	v_bfe_u32 v224, v220, 4, 2
	v_xor_b32_e32 v223, v223, v224
	v_lshlrev_b32_e32 v223, 4, v223
	v_and_b32_e32 v224, 1, v221
	v_lshrrev_b32_e32 v225, 1, v221
	v_lshlrev_b32_e32 v224, 5, v224
	v_lshl_add_u32 v224, v225, 7, v224
	v_add_u32_e32 v224, v224, v222
	v_lshl_add_u32 v225, v221, 5, v222
	v_lshl_or_b32 v210, v224, 11, v223
	v_lshl_or_b32 v216, v225, 11, v223
	v_xor_b32_e32 v224, 64, v210
	v_xor_b32_e32 v225, 64, v216
	v_add_u32_e32 v211, 0x3c00, v224
	v_add_u32_e32 v217, 0x3c00, v225
	v_add_u32_e32 v212, 0x7800, v210
	v_add_u32_e32 v218, 0x7800, v216
	v_add_u32_e32 v213, 0xb400, v224
	v_add_u32_e32 v219, 0xb400, v225
	v_and_b32_e32 v222, 31, v220
	v_lshrrev_b32_e32 v223, 5, v220
	v_bfe_u32 v224, v220, 1, 3
	v_xor_b32_e32 v223, v223, v224
	v_lshlrev_b32_e32 v223, 4, v223
	v_lshrrev_b32_e32 v224, 1, v221
	v_and_b32_e32 v225, 1, v221
	v_lshl_add_u32 v224, v224, 6, v222
	v_lshl_add_u32 v225, v225, 6, v222
	v_lshl_or_b32 v202, v224, 7, v223
	v_lshl_or_b32 v206, v225, 7, v223
	v_xor_b32_e32 v203, 32, v202
	v_xor_b32_e32 v207, 32, v206
	v_xor_b32_e32 v204, 64, v202
	v_xor_b32_e32 v208, 64, v206
	v_xor_b32_e32 v205, 96, v202
	v_xor_b32_e32 v209, 96, v206
	s_lshl_b32 s13, s13, 12
	s_sub_u32 s10, s4, 0x80
	s_subb_u32 s11, s5, 0
	s_add_u32 s8, s2, 0x1ff80
	s_addc_u32 s9, s3, 0
	s_sub_u32 s6, s2, 0x80
	s_subb_u32 s7, s3, 0
	s_mov_b32 s12, 0
	v_mov_b32_e32 v112, 0
	v_mov_b32_e32 v113, 0
	v_mov_b32_e32 v114, 0
	v_mov_b32_e32 v115, 0
	v_mov_b32_e32 v116, 0
	v_mov_b32_e32 v117, 0
	v_mov_b32_e32 v118, 0
	v_mov_b32_e32 v119, 0
	v_mov_b32_e32 v120, 0
	v_mov_b32_e32 v121, 0
	v_mov_b32_e32 v122, 0
	v_mov_b32_e32 v123, 0
	v_mov_b32_e32 v124, 0
	v_mov_b32_e32 v125, 0
	v_mov_b32_e32 v126, 0
	v_mov_b32_e32 v127, 0
	v_mov_b32_e32 v64, 0
	v_mov_b32_e32 v65, 0
	v_mov_b32_e32 v66, 0
	v_mov_b32_e32 v67, 0
	v_mov_b32_e32 v68, 0
	v_mov_b32_e32 v69, 0
	v_mov_b32_e32 v70, 0
	v_mov_b32_e32 v71, 0
	v_mov_b32_e32 v72, 0
	v_mov_b32_e32 v73, 0
	v_mov_b32_e32 v74, 0
	v_mov_b32_e32 v75, 0
	v_mov_b32_e32 v76, 0
	v_mov_b32_e32 v77, 0
	v_mov_b32_e32 v78, 0
	v_mov_b32_e32 v79, 0
	v_mov_b32_e32 v96, 0
	v_mov_b32_e32 v97, 0
	v_mov_b32_e32 v98, 0
	v_mov_b32_e32 v99, 0
	v_mov_b32_e32 v100, 0
	v_mov_b32_e32 v101, 0
	v_mov_b32_e32 v102, 0
	v_mov_b32_e32 v103, 0
	v_mov_b32_e32 v104, 0
	v_mov_b32_e32 v105, 0
	v_mov_b32_e32 v106, 0
	v_mov_b32_e32 v107, 0
	v_mov_b32_e32 v108, 0
	v_mov_b32_e32 v109, 0
	v_mov_b32_e32 v110, 0
	v_mov_b32_e32 v111, 0
	v_mov_b32_e32 v32, 0
	v_mov_b32_e32 v33, 0
	v_mov_b32_e32 v34, 0
	v_mov_b32_e32 v35, 0
	v_mov_b32_e32 v36, 0
	v_mov_b32_e32 v37, 0
	v_mov_b32_e32 v38, 0
	v_mov_b32_e32 v39, 0
	v_mov_b32_e32 v40, 0
	v_mov_b32_e32 v41, 0
	v_mov_b32_e32 v42, 0
	v_mov_b32_e32 v43, 0
	v_mov_b32_e32 v44, 0
	v_mov_b32_e32 v45, 0
	v_mov_b32_e32 v46, 0
	v_mov_b32_e32 v47, 0
	v_mov_b32_e32 v80, 0
	v_mov_b32_e32 v81, 0
	v_mov_b32_e32 v82, 0
	v_mov_b32_e32 v83, 0
	v_mov_b32_e32 v84, 0
	v_mov_b32_e32 v85, 0
	v_mov_b32_e32 v86, 0
	v_mov_b32_e32 v87, 0
	v_mov_b32_e32 v88, 0
	v_mov_b32_e32 v89, 0
	v_mov_b32_e32 v90, 0
	v_mov_b32_e32 v91, 0
	v_mov_b32_e32 v92, 0
	v_mov_b32_e32 v93, 0
	v_mov_b32_e32 v94, 0
	v_mov_b32_e32 v95, 0
	v_mov_b32_e32 v16, 0
	v_mov_b32_e32 v17, 0
	v_mov_b32_e32 v18, 0
	v_mov_b32_e32 v19, 0
	v_mov_b32_e32 v20, 0
	v_mov_b32_e32 v21, 0
	v_mov_b32_e32 v22, 0
	v_mov_b32_e32 v23, 0
	v_mov_b32_e32 v24, 0
	v_mov_b32_e32 v25, 0
	v_mov_b32_e32 v26, 0
	v_mov_b32_e32 v27, 0
	v_mov_b32_e32 v28, 0
	v_mov_b32_e32 v29, 0
	v_mov_b32_e32 v30, 0
	v_mov_b32_e32 v31, 0
	v_mov_b32_e32 v48, 0
	v_mov_b32_e32 v49, 0
	v_mov_b32_e32 v50, 0
	v_mov_b32_e32 v51, 0
	v_mov_b32_e32 v52, 0
	v_mov_b32_e32 v53, 0
	v_mov_b32_e32 v54, 0
	v_mov_b32_e32 v55, 0
	v_mov_b32_e32 v56, 0
	v_mov_b32_e32 v57, 0
	v_mov_b32_e32 v58, 0
	v_mov_b32_e32 v59, 0
	v_mov_b32_e32 v60, 0
	v_mov_b32_e32 v61, 0
	v_mov_b32_e32 v62, 0
	v_mov_b32_e32 v63, 0
	v_mov_b32_e32 v0, 0
	v_mov_b32_e32 v1, 0
	v_mov_b32_e32 v2, 0
	v_mov_b32_e32 v3, 0
	v_mov_b32_e32 v4, 0
	v_mov_b32_e32 v5, 0
	v_mov_b32_e32 v6, 0
	v_mov_b32_e32 v7, 0
	v_mov_b32_e32 v8, 0
	v_mov_b32_e32 v9, 0
	v_mov_b32_e32 v10, 0
	v_mov_b32_e32 v11, 0
	v_mov_b32_e32 v12, 0
	v_mov_b32_e32 v13, 0
	v_mov_b32_e32 v14, 0
	v_mov_b32_e32 v15, 0
	s_waitcnt lgkmcnt(0)
	s_barrier
	s_add_u32 s10, s10, 0x80
	s_addc_u32 s11, s11, 0
	s_add_u32 m0, s13, 0
	s_nop 0
	global_load_lds_dwordx4 v216, s[10:11] sc1
	global_load_lds_dwordx4 v217, s[10:11] offset:1024 sc1
	global_load_lds_dwordx4 v218, s[10:11] offset:2048 sc1
	global_load_lds_dwordx4 v219, s[10:11] offset:3072 sc1
	s_add_u32 s6, s6, 0x80
	s_addc_u32 s7, s7, 0
	s_add_u32 m0, s13, 32768
	s_nop 0
	global_load_lds_dwordx4 v210, s[6:7]
	global_load_lds_dwordx4 v211, s[6:7] offset:1024
	global_load_lds_dwordx4 v212, s[6:7] offset:2048
	global_load_lds_dwordx4 v213, s[6:7] offset:3072
; #define GLOAD(dst, kt_) _Pragma("unroll") for (int i = 0; i < NCH; ++i) { dst[i] = (i < NCHW) ? ldw(i, tid >> 3, (kt_) * 64 + (tid & 7) * 8) : ldx(i - NCHW, tid >> 3, (kt_) * 64 + (tid & 7) * 8); }
; #define LSTORE(src, base) _Pragma("unroll") for (int i = 0; i < NCH; ++i) { const int c = tid + 256 * i; *(u32x4*)((base) + (c >> 3) * 144 + (c & 7) * 16) = src[i]; }
; template <int WGN, int INS, int IMS, bool DB, class LdW, class LdX>
; DI void gemm_core(f32x16 (&acc)[INS][IMS], const int KT, LdW ldw, LdX ldx, char* lds, const int tid) {
;     ...
;     for (int kt = 0; kt < KT; kt += 2) {
;       if (kt + 2 < KT) { GLOAD(preA, kt + 2) }
;       COMPUTE_PIPE(lds)
;       LSTORE(preB, lds + BUFB)
;       __syncthreads();
;       if (kt + 3 < KT) { GLOAD(preB, kt + 3) }
;       COMPUTE_PIPE(lds + BUFB)
;       if (kt + 2 < KT) { LSTORE(preA, lds) }
;       __syncthreads();
;     }
.Lgd_loop:
	s_waitcnt vmcnt(0)
	s_barrier
	ds_read_b128 v[160:163], v206 offset:0
	ds_read_b128 v[236:239], v206 offset:4096
	ds_read_b128 v[128:131], v202 offset:32768
	ds_read_b128 v[144:147], v202 offset:36864
	ds_read_b128 v[164:167], v207 offset:0
	ds_read_b128 v[240:243], v207 offset:4096
	ds_read_b128 v[132:135], v203 offset:32768
	ds_read_b128 v[148:151], v203 offset:36864
	s_add_u32 s8, s8, 0x80
	s_addc_u32 s9, s9, 0
	s_add_u32 m0, s13, 49152
	s_nop 0
	global_load_lds_dwordx4 v210, s[8:9]
	global_load_lds_dwordx4 v211, s[8:9] offset:1024
	global_load_lds_dwordx4 v212, s[8:9] offset:2048
	global_load_lds_dwordx4 v213, s[8:9] offset:3072
	s_add_u32 s10, s10, 0x80
	s_addc_u32 s11, s11, 0
	s_add_u32 m0, s13, 16384
	s_nop 0
	global_load_lds_dwordx4 v216, s[10:11] sc1
	global_load_lds_dwordx4 v217, s[10:11] offset:1024 sc1
	global_load_lds_dwordx4 v218, s[10:11] offset:2048 sc1
	global_load_lds_dwordx4 v219, s[10:11] offset:3072 sc1
	s_waitcnt lgkmcnt(4)
	v_mfma_f32_32x32x16_bf16 v[112:127], v[128:131], v[160:163], v[112:127]
	v_mfma_f32_32x32x16_bf16 v[64:79], v[128:131], v[236:239], v[64:79]
	ds_read_b128 v[168:171], v208 offset:0
	ds_read_b128 v[244:247], v208 offset:4096
	ds_read_b128 v[136:139], v204 offset:32768
	ds_read_b128 v[152:155], v204 offset:36864
	v_mfma_f32_32x32x16_bf16 v[96:111], v[144:147], v[160:163], v[96:111]
	v_mfma_f32_32x32x16_bf16 v[32:47], v[144:147], v[236:239], v[32:47]
	s_waitcnt lgkmcnt(4)
	v_mfma_f32_32x32x16_bf16 v[112:127], v[132:135], v[164:167], v[112:127]
	v_mfma_f32_32x32x16_bf16 v[64:79], v[132:135], v[240:243], v[64:79]
	ds_read_b128 v[172:175], v209 offset:0
	ds_read_b128 v[248:251], v209 offset:4096
	ds_read_b128 v[140:143], v205 offset:32768
	ds_read_b128 v[156:159], v205 offset:36864
	v_mfma_f32_32x32x16_bf16 v[96:111], v[148:151], v[164:167], v[96:111]
	v_mfma_f32_32x32x16_bf16 v[32:47], v[148:151], v[240:243], v[32:47]
	s_waitcnt lgkmcnt(4)
	v_mfma_f32_32x32x16_bf16 v[112:127], v[136:139], v[168:171], v[112:127]
	v_mfma_f32_32x32x16_bf16 v[64:79], v[136:139], v[244:247], v[64:79]
	v_mfma_f32_32x32x16_bf16 v[96:111], v[152:155], v[168:171], v[96:111]
	v_mfma_f32_32x32x16_bf16 v[32:47], v[152:155], v[244:247], v[32:47]
	s_waitcnt lgkmcnt(0)
	v_mfma_f32_32x32x16_bf16 v[112:127], v[140:143], v[172:175], v[112:127]
	v_mfma_f32_32x32x16_bf16 v[64:79], v[140:143], v[248:251], v[64:79]
	v_mfma_f32_32x32x16_bf16 v[96:111], v[156:159], v[172:175], v[96:111]
	v_mfma_f32_32x32x16_bf16 v[32:47], v[156:159], v[248:251], v[32:47]
	s_waitcnt vmcnt(4)
	s_barrier
	ds_read_b128 v[128:131], v202 offset:49152
	ds_read_b128 v[144:147], v202 offset:53248
	ds_read_b128 v[132:135], v203 offset:49152
	ds_read_b128 v[148:151], v203 offset:53248
	ds_read_b128 v[136:139], v204 offset:49152
	ds_read_b128 v[152:155], v204 offset:53248
	ds_read_b128 v[140:143], v205 offset:49152
	ds_read_b128 v[156:159], v205 offset:53248
	s_add_u32 s6, s6, 0x80
	s_addc_u32 s7, s7, 0
	s_add_u32 m0, s13, 32768
	s_nop 0
	global_load_lds_dwordx4 v210, s[6:7]
	global_load_lds_dwordx4 v211, s[6:7] offset:1024
	global_load_lds_dwordx4 v212, s[6:7] offset:2048
	global_load_lds_dwordx4 v213, s[6:7] offset:3072
	s_waitcnt lgkmcnt(6)
	v_mfma_f32_32x32x16_bf16 v[80:95], v[128:131], v[160:163], v[80:95]
	v_mfma_f32_32x32x16_bf16 v[16:31], v[128:131], v[236:239], v[16:31]
	v_mfma_f32_32x32x16_bf16 v[48:63], v[144:147], v[160:163], v[48:63]
	v_mfma_f32_32x32x16_bf16 v[0:15], v[144:147], v[236:239], v[0:15]
	s_waitcnt lgkmcnt(4)
	v_mfma_f32_32x32x16_bf16 v[80:95], v[132:135], v[164:167], v[80:95]
	v_mfma_f32_32x32x16_bf16 v[16:31], v[132:135], v[240:243], v[16:31]
	v_mfma_f32_32x32x16_bf16 v[48:63], v[148:151], v[164:167], v[48:63]
	v_mfma_f32_32x32x16_bf16 v[0:15], v[148:151], v[240:243], v[0:15]
	s_waitcnt lgkmcnt(2)
	v_mfma_f32_32x32x16_bf16 v[80:95], v[136:139], v[168:171], v[80:95]
	v_mfma_f32_32x32x16_bf16 v[16:31], v[136:139], v[244:247], v[16:31]
	v_mfma_f32_32x32x16_bf16 v[48:63], v[152:155], v[168:171], v[48:63]
	v_mfma_f32_32x32x16_bf16 v[0:15], v[152:155], v[244:247], v[0:15]
	s_waitcnt lgkmcnt(0)
	v_mfma_f32_32x32x16_bf16 v[80:95], v[140:143], v[172:175], v[80:95]
	v_mfma_f32_32x32x16_bf16 v[16:31], v[140:143], v[248:251], v[16:31]
	v_mfma_f32_32x32x16_bf16 v[48:63], v[156:159], v[172:175], v[48:63]
	v_mfma_f32_32x32x16_bf16 v[0:15], v[156:159], v[248:251], v[0:15]
	s_waitcnt vmcnt(0)
	s_barrier
	ds_read_b128 v[160:163], v206 offset:16384
	ds_read_b128 v[236:239], v206 offset:20480
	ds_read_b128 v[128:131], v202 offset:32768
	ds_read_b128 v[144:147], v202 offset:36864
	ds_read_b128 v[164:167], v207 offset:16384
	ds_read_b128 v[240:243], v207 offset:20480
	ds_read_b128 v[132:135], v203 offset:32768
	ds_read_b128 v[148:151], v203 offset:36864
	s_add_u32 s8, s8, 0x80
	s_addc_u32 s9, s9, 0
	s_add_u32 m0, s13, 49152
	s_nop 0
	global_load_lds_dwordx4 v210, s[8:9]
	global_load_lds_dwordx4 v211, s[8:9] offset:1024
	global_load_lds_dwordx4 v212, s[8:9] offset:2048
	global_load_lds_dwordx4 v213, s[8:9] offset:3072
	s_cmp_eq_u32 s12, 7
	s_cbranch_scc1 .Lgd_skipx
	s_add_u32 s10, s10, 0x80
	s_addc_u32 s11, s11, 0
	s_add_u32 m0, s13, 0
	s_nop 0
	global_load_lds_dwordx4 v216, s[10:11] sc1
	global_load_lds_dwordx4 v217, s[10:11] offset:1024 sc1
	global_load_lds_dwordx4 v218, s[10:11] offset:2048 sc1
	global_load_lds_dwordx4 v219, s[10:11] offset:3072 sc1
; #define GLOAD(dst, kt_) _Pragma("unroll") for (int i = 0; i < NCH; ++i) { dst[i] = (i < NCHW) ? ldw(i, tid >> 3, (kt_) * 64 + (tid & 7) * 8) : ldx(i - NCHW, tid >> 3, (kt_) * 64 + (tid & 7) * 8); }
; #define LSTORE(src, base) _Pragma("unroll") for (int i = 0; i < NCH; ++i) { const int c = tid + 256 * i; *(u32x4*)((base) + (c >> 3) * 144 + (c & 7) * 16) = src[i]; }
; template <int WGN, int INS, int IMS, bool DB, class LdW, class LdX>
; DI void gemm_core(f32x16 (&acc)[INS][IMS], const int KT, LdW ldw, LdX ldx, char* lds, const int tid) {
;     ...
;     for (int kt = 0; kt < KT; kt += 2) {
;       if (kt + 2 < KT) { GLOAD(preA, kt + 2) }
;       COMPUTE_PIPE(lds)
;       LSTORE(preB, lds + BUFB)
;       __syncthreads();
;       if (kt + 3 < KT) { GLOAD(preB, kt + 3) }
;       COMPUTE_PIPE(lds + BUFB)
;       if (kt + 2 < KT) { LSTORE(preA, lds) }
;       __syncthreads();
;     }
.Lgd_skipx:
	s_waitcnt lgkmcnt(4)
	v_mfma_f32_32x32x16_bf16 v[112:127], v[128:131], v[160:163], v[112:127]
	v_mfma_f32_32x32x16_bf16 v[64:79], v[128:131], v[236:239], v[64:79]
	ds_read_b128 v[168:171], v208 offset:16384
	ds_read_b128 v[244:247], v208 offset:20480
	ds_read_b128 v[136:139], v204 offset:32768
	ds_read_b128 v[152:155], v204 offset:36864
	v_mfma_f32_32x32x16_bf16 v[96:111], v[144:147], v[160:163], v[96:111]
	v_mfma_f32_32x32x16_bf16 v[32:47], v[144:147], v[236:239], v[32:47]
	s_waitcnt lgkmcnt(4)
	v_mfma_f32_32x32x16_bf16 v[112:127], v[132:135], v[164:167], v[112:127]
	v_mfma_f32_32x32x16_bf16 v[64:79], v[132:135], v[240:243], v[64:79]
	ds_read_b128 v[172:175], v209 offset:16384
	ds_read_b128 v[248:251], v209 offset:20480
	ds_read_b128 v[140:143], v205 offset:32768
	ds_read_b128 v[156:159], v205 offset:36864
	v_mfma_f32_32x32x16_bf16 v[96:111], v[148:151], v[164:167], v[96:111]
	v_mfma_f32_32x32x16_bf16 v[32:47], v[148:151], v[240:243], v[32:47]
	s_waitcnt lgkmcnt(4)
	v_mfma_f32_32x32x16_bf16 v[112:127], v[136:139], v[168:171], v[112:127]
	v_mfma_f32_32x32x16_bf16 v[64:79], v[136:139], v[244:247], v[64:79]
	v_mfma_f32_32x32x16_bf16 v[96:111], v[152:155], v[168:171], v[96:111]
	v_mfma_f32_32x32x16_bf16 v[32:47], v[152:155], v[244:247], v[32:47]
	s_waitcnt lgkmcnt(0)
	v_mfma_f32_32x32x16_bf16 v[112:127], v[140:143], v[172:175], v[112:127]
	v_mfma_f32_32x32x16_bf16 v[64:79], v[140:143], v[248:251], v[64:79]
	v_mfma_f32_32x32x16_bf16 v[96:111], v[156:159], v[172:175], v[96:111]
	v_mfma_f32_32x32x16_bf16 v[32:47], v[156:159], v[248:251], v[32:47]
	s_cmp_eq_u32 s12, 7
	s_cbranch_scc1 .Lgd_lastp1
	s_waitcnt vmcnt(4)
	s_barrier
	ds_read_b128 v[128:131], v202 offset:49152
	ds_read_b128 v[144:147], v202 offset:53248
	ds_read_b128 v[132:135], v203 offset:49152
	ds_read_b128 v[148:151], v203 offset:53248
	ds_read_b128 v[136:139], v204 offset:49152
	ds_read_b128 v[152:155], v204 offset:53248
	ds_read_b128 v[140:143], v205 offset:49152
	ds_read_b128 v[156:159], v205 offset:53248
	s_add_u32 s6, s6, 0x80
	s_addc_u32 s7, s7, 0
	s_add_u32 m0, s13, 32768
	s_nop 0
	global_load_lds_dwordx4 v210, s[6:7]
	global_load_lds_dwordx4 v211, s[6:7] offset:1024
	global_load_lds_dwordx4 v212, s[6:7] offset:2048
	global_load_lds_dwordx4 v213, s[6:7] offset:3072
	s_branch .Lgd_p1c

; DI void outproj_item(const Params& p, int l, int it, char* lds) {
;     ...
;   const int lane = tid & 63, wid = tid >> 6, l31 = lane & 31, hi = lane >> 5, wn = wid >> 1, wm = wid & 1;
;   u16* outb = (u16*)(ws_ + OFF_OUTB);
;   float* ssq = (float*)(ws_ + OFF_SSQ);
;   constexpr int RS = 256 * 2 + 16;
;   __syncthreads();
; #pragma unroll
;   for (int im = 0; im < 2; ++im) {
;     const int tl = wm * 64 + im * 32 + l31;
;     float ss = 0.f;
; #pragma unroll
;     for (int in = 0; in < 4; ++in)
; #pragma unroll
;       for (int g = 0; g < 4; ++g) {
;         const int n = wn * 128 + in * 32 + 8 * g + 4 * hi;
;         const float o0 = acc[in][im][4 * g], o1 = acc[in][im][4 * g + 1], o2 = acc[in][im][4 * g + 2], o3 = acc[in][im][4 * g + 3];
;         ss += o0 * o0 + o1 * o1 + o2 * o2 + o3 * o3;
;         u32x2 v; v[0] = pk2(o0, o1); v[1] = pk2(o2, o3);
;         *(u32x2*)(lds + tl * RS + n * 2) = v;
;       }
;     ss += __shfl_xor(ss, 32, 64);
;     if (hi == 0) ssq[((size_t)mt * 128 + tl) * 16 + nt * 2 + wn] = ss;
;   }
.Lgd_p1c:
	s_waitcnt lgkmcnt(6)
	v_mfma_f32_32x32x16_bf16 v[80:95], v[128:131], v[160:163], v[80:95]
	v_mfma_f32_32x32x16_bf16 v[16:31], v[128:131], v[236:239], v[16:31]
	v_mfma_f32_32x32x16_bf16 v[48:63], v[144:147], v[160:163], v[48:63]
	v_mfma_f32_32x32x16_bf16 v[0:15], v[144:147], v[236:239], v[0:15]
	s_waitcnt lgkmcnt(4)
	v_mfma_f32_32x32x16_bf16 v[80:95], v[132:135], v[164:167], v[80:95]
	v_mfma_f32_32x32x16_bf16 v[16:31], v[132:135], v[240:243], v[16:31]
	v_mfma_f32_32x32x16_bf16 v[48:63], v[148:151], v[164:167], v[48:63]
	v_mfma_f32_32x32x16_bf16 v[0:15], v[148:151], v[240:243], v[0:15]
	s_waitcnt lgkmcnt(2)
	v_mfma_f32_32x32x16_bf16 v[80:95], v[136:139], v[168:171], v[80:95]
	v_mfma_f32_32x32x16_bf16 v[16:31], v[136:139], v[244:247], v[16:31]
	v_mfma_f32_32x32x16_bf16 v[48:63], v[152:155], v[168:171], v[48:63]
	v_mfma_f32_32x32x16_bf16 v[0:15], v[152:155], v[244:247], v[0:15]
	s_waitcnt lgkmcnt(0)
	v_mfma_f32_32x32x16_bf16 v[80:95], v[140:143], v[172:175], v[80:95]
	v_mfma_f32_32x32x16_bf16 v[16:31], v[140:143], v[248:251], v[16:31]
	v_mfma_f32_32x32x16_bf16 v[48:63], v[156:159], v[172:175], v[48:63]
	v_mfma_f32_32x32x16_bf16 v[0:15], v[156:159], v[248:251], v[0:15]
	s_add_i32 s12, s12, 1
	s_cmp_lg_u32 s12, 8
	s_cbranch_scc1 .Lgd_loop
	s_nop 15
	s_barrier
	s_lshl_b32 s2, s30, 1
	s_ashr_i32 s3, s2, 31
	s_lshl_b64 s[2:3], s[2:3], 2
	s_add_u32 s2, s28, s2
	s_addc_u32 s3, s29, s3
	s_barrier
	s_nop 9
	v_mul_f32_e32 v133, v113, v113
	v_fmac_f32_e32 v133, v112, v112
	v_fmac_f32_e32 v133, v114, v114
	v_cvt_pk_bf16_f32 v112, v112, v113
	v_cvt_pk_bf16_f32 v113, v114, v115
	v_mul_f32_e32 v114, v117, v117
	v_fmac_f32_e32 v114, v116, v116
	v_lshlrev_b32_e32 v130, 1, v181
	v_bfe_u32 v129, v181, 5, 1
	v_and_b32_e32 v130, 0xffffff00, v130
	v_and_b32_e32 v132, 64, v195
	v_fmac_f32_e32 v114, v118, v118
	v_lshl_or_b32 v131, v129, 3, v130
	v_xor_b32_e32 v130, 32, v195
	v_add_u32_e32 v132, 64, v132
	v_fmac_f32_e32 v133, v115, v115
	v_fmac_f32_e32 v114, v119, v119
	v_cmp_lt_i32_e32 vcc, v130, v132
	v_mad_u32_u24 v132, v183, s73, v131
	v_add_f32_e32 v133, v133, v114
	v_cvt_pk_bf16_f32 v114, v116, v117
	v_cvt_pk_bf16_f32 v115, v118, v119
	ds_write2_b64 v132, v[112:113], v[114:115] offset1:2
	v_mul_f32_e32 v112, v121, v121
	v_fmac_f32_e32 v112, v120, v120
	v_mul_f32_e32 v115, v125, v125
	v_fmac_f32_e32 v112, v122, v122
	v_fmac_f32_e32 v115, v124, v124
	v_fmac_f32_e32 v112, v123, v123
	v_fmac_f32_e32 v115, v126, v126
	v_add_f32_e32 v114, v112, v133
	v_fmac_f32_e32 v115, v127, v127
	v_cvt_pk_bf16_f32 v112, v120, v121
	v_cvt_pk_bf16_f32 v113, v122, v123
	v_add_f32_e32 v116, v115, v114
	v_cvt_pk_bf16_f32 v114, v124, v125
	v_cvt_pk_bf16_f32 v115, v126, v127
	ds_write2_b64 v132, v[112:113], v[114:115] offset0:4 offset1:6
	v_mul_f32_e32 v112, v97, v97
	v_fmac_f32_e32 v112, v96, v96
	v_fmac_f32_e32 v112, v98, v98
	v_cvt_pk_bf16_f32 v96, v96, v97
	v_cvt_pk_bf16_f32 v97, v98, v99
	v_mul_f32_e32 v98, v101, v101
	v_fmac_f32_e32 v98, v100, v100
	v_fmac_f32_e32 v112, v99, v99
	v_fmac_f32_e32 v98, v102, v102
	v_add_f32_e32 v112, v112, v116
	v_fmac_f32_e32 v98, v103, v103
	v_add_f32_e32 v112, v98, v112
	v_cvt_pk_bf16_f32 v98, v100, v101
	v_cvt_pk_bf16_f32 v99, v102, v103
	ds_write2_b64 v132, v[96:97], v[98:99] offset0:8 offset1:10
	v_mul_f32_e32 v96, v105, v105
	v_fmac_f32_e32 v96, v104, v104
	v_mul_f32_e32 v99, v109, v109
	v_fmac_f32_e32 v96, v106, v106
	v_fmac_f32_e32 v99, v108, v108
	v_fmac_f32_e32 v96, v107, v107
	v_fmac_f32_e32 v99, v110, v110
	v_add_f32_e32 v98, v96, v112
	v_fmac_f32_e32 v99, v111, v111
	v_cvt_pk_bf16_f32 v96, v104, v105
	v_cvt_pk_bf16_f32 v97, v106, v107
	v_add_f32_e32 v100, v99, v98
	v_cvt_pk_bf16_f32 v98, v108, v109
	v_cvt_pk_bf16_f32 v99, v110, v111
	ds_write2_b64 v132, v[96:97], v[98:99] offset0:12 offset1:14
	v_mul_f32_e32 v96, v81, v81
	v_fmac_f32_e32 v96, v80, v80
	v_fmac_f32_e32 v96, v82, v82
	v_cvt_pk_bf16_f32 v80, v80, v81
	v_cvt_pk_bf16_f32 v81, v82, v83
	v_mul_f32_e32 v82, v85, v85
	v_fmac_f32_e32 v82, v84, v84
	v_fmac_f32_e32 v96, v83, v83
	v_fmac_f32_e32 v82, v86, v86
	v_add_f32_e32 v96, v96, v100
	v_fmac_f32_e32 v82, v87, v87
	v_add_f32_e32 v96, v82, v96
	v_cvt_pk_bf16_f32 v82, v84, v85
	v_cvt_pk_bf16_f32 v83, v86, v87
	ds_write2_b64 v132, v[80:81], v[82:83] offset0:16 offset1:18
	v_mul_f32_e32 v80, v89, v89
	v_fmac_f32_e32 v80, v88, v88
	v_mul_f32_e32 v83, v93, v93
	v_fmac_f32_e32 v80, v90, v90
	v_fmac_f32_e32 v83, v92, v92
	v_fmac_f32_e32 v80, v91, v91
	v_fmac_f32_e32 v83, v94, v94
	v_add_f32_e32 v82, v80, v96
	v_fmac_f32_e32 v83, v95, v95
	v_cvt_pk_bf16_f32 v80, v88, v89
	v_cvt_pk_bf16_f32 v81, v90, v91
	v_add_f32_e32 v84, v83, v82
	v_cvt_pk_bf16_f32 v82, v92, v93
	v_cvt_pk_bf16_f32 v83, v94, v95
	ds_write2_b64 v132, v[80:81], v[82:83] offset0:20 offset1:22
	v_mul_f32_e32 v80, v49, v49
	v_fmac_f32_e32 v80, v48, v48
	v_fmac_f32_e32 v80, v50, v50
	v_cvt_pk_bf16_f32 v48, v48, v49
	v_cvt_pk_bf16_f32 v49, v50, v51
	v_mul_f32_e32 v50, v53, v53
	v_fmac_f32_e32 v50, v52, v52
	v_fmac_f32_e32 v80, v51, v51
	v_fmac_f32_e32 v50, v54, v54
	v_add_f32_e32 v80, v80, v84
	v_fmac_f32_e32 v50, v55, v55
	v_add_f32_e32 v80, v50, v80
	v_cvt_pk_bf16_f32 v50, v52, v53
	v_cvt_pk_bf16_f32 v51, v54, v55
	ds_write2_b64 v132, v[48:49], v[50:51] offset0:24 offset1:26
	v_mul_f32_e32 v48, v57, v57
	v_fmac_f32_e32 v48, v56, v56
	v_mul_f32_e32 v49, v61, v61
	v_fmac_f32_e32 v48, v58, v58
	v_fmac_f32_e32 v49, v60, v60
	v_fmac_f32_e32 v48, v59, v59
	v_fmac_f32_e32 v49, v62, v62
	v_cndmask_b32_e32 v130, v195, v130, vcc
	v_add_f32_e32 v48, v48, v80
	v_fmac_f32_e32 v49, v63, v63
	v_lshlrev_b32_e32 v130, 2, v130
	v_add_f32_e32 v48, v49, v48
	ds_bpermute_b32 v49, v130, v48
	v_ashrrev_i32_e32 v128, 7, v181
	v_cmp_eq_u32_e32 vcc, 0, v129
	v_ashrrev_i32_e32 v129, 31, v128
	v_lshl_add_u64 v[128:129], v[128:129], 2, s[2:3]
	s_mov_b64 s[2:3], 0xb250000
	v_lshl_add_u64 v[128:129], v[128:129], 0, s[2:3]
	v_cvt_pk_bf16_f32 v50, v56, v57
	v_cvt_pk_bf16_f32 v51, v58, v59
	v_cvt_pk_bf16_f32 v52, v60, v61
	v_cvt_pk_bf16_f32 v53, v62, v63
	ds_write2_b64 v132, v[50:51], v[52:53] offset0:28 offset1:30
	s_and_saveexec_b64 s[2:3], vcc
	s_cbranch_execz .LBB0_537
	v_or_b32_e32 v50, s80, v183
	v_lshlrev_b32_e32 v178, 6, v50
	v_lshl_add_u64 v[50:51], v[128:129], 0, v[178:179]
	s_waitcnt lgkmcnt(1)
	v_add_f32_e32 v48, v48, v49
	global_store_dword v[50:51], v48, off
